# setprio flips removed only in the P5 (gate/up) K-loop
# speedup vs baseline: 1.0051x; 1.0001x over previous
.LBB0_872:
	v_add_u32_e32 v162, s73, v140
	v_add_u32_e32 v178, s74, v140
	ds_read_b128 v[150:153], v162
	ds_read_b128 v[154:157], v162 offset:1024
	ds_read_b128 v[158:161], v162 offset:2048
	ds_read_b128 v[162:165], v162 offset:3072
	ds_read_b128 v[166:169], v178
	ds_read_b128 v[170:173], v178 offset:1024
	ds_read_b128 v[174:177], v178 offset:2048
	ds_read_b128 v[178:181], v178 offset:3072
	s_add_i32 s77, s52, 2
	s_add_u32 s50, s34, 0xfffc0080
	s_addc_u32 s51, s35, -1
	s_cmp_eq_u32 s70, s52
	s_cselect_b32 s52, s30, s21
	s_cselect_b32 s55, s29, s51
	s_cselect_b32 s54, s28, s50
	s_cselect_b32 s53, s31, s23
	v_lshl_add_u64 v[214:215], s[34:35], 0, v[132:133]
	s_add_i32 m0, s60, 0xc000
	ds_read_b128 v[182:185], v149
	ds_read_b128 v[186:189], v149 offset:1024
	ds_read_b128 v[190:193], v149 offset:2048
	ds_read_b128 v[194:197], v149 offset:3072
	ds_read_b128 v[198:201], v149 offset:4096
	ds_read_b128 v[202:205], v149 offset:5120
	ds_read_b128 v[206:209], v149 offset:6144
	ds_read_b128 v[210:213], v149 offset:7168
	global_load_lds_dwordx4 v[214:215], off
	v_lshl_add_u64 v[214:215], s[34:35], 0, v[134:135]
	s_add_i32 m0, s60, 0xe000
	s_nop 0
	global_load_lds_dwordx4 v[214:215], off
	s_waitcnt vmcnt(8)
	s_waitcnt lgkmcnt(0)
	s_barrier
	s_waitcnt lgkmcnt(0)
	v_mfma_f32_16x16x32_bf16 v[78:81], v[150:153], v[182:185], v[78:81]
	v_mfma_f32_16x16x32_bf16 v[14:17], v[158:161], v[182:185], v[14:17]
	v_mfma_f32_16x16x32_bf16 v[66:69], v[150:153], v[190:193], v[66:69]
	v_mfma_f32_16x16x32_bf16 v[2:5], v[158:161], v[190:193], v[2:5]
	v_mfma_f32_16x16x32_bf16 v[70:73], v[150:153], v[198:201], v[70:73]
	v_mfma_f32_16x16x32_bf16 v[6:9], v[158:161], v[198:201], v[6:9]
	v_mfma_f32_16x16x32_bf16 v[74:77], v[150:153], v[206:209], v[74:77]
	v_mfma_f32_16x16x32_bf16 v[10:13], v[158:161], v[206:209], v[10:13]
	v_mfma_f32_16x16x32_bf16 v[78:81], v[154:157], v[186:189], v[78:81]
	v_mfma_f32_16x16x32_bf16 v[14:17], v[162:165], v[186:189], v[14:17]
	v_mfma_f32_16x16x32_bf16 v[66:69], v[154:157], v[194:197], v[66:69]
	v_mfma_f32_16x16x32_bf16 v[2:5], v[162:165], v[194:197], v[2:5]
	v_mfma_f32_16x16x32_bf16 v[70:73], v[154:157], v[202:205], v[70:73]
	v_mfma_f32_16x16x32_bf16 v[6:9], v[162:165], v[202:205], v[6:9]
	v_mfma_f32_16x16x32_bf16 v[74:77], v[154:157], v[210:213], v[74:77]
	v_mfma_f32_16x16x32_bf16 v[10:13], v[162:165], v[210:213], v[10:13]
	v_mfma_f32_16x16x32_bf16 v[98:101], v[166:169], v[182:185], v[98:101]
	v_mfma_f32_16x16x32_bf16 v[34:37], v[174:177], v[182:185], v[34:37]
	v_mfma_f32_16x16x32_bf16 v[82:85], v[166:169], v[190:193], v[82:85]
	v_mfma_f32_16x16x32_bf16 v[18:21], v[174:177], v[190:193], v[18:21]
	v_mfma_f32_16x16x32_bf16 v[86:89], v[166:169], v[198:201], v[86:89]
	v_mfma_f32_16x16x32_bf16 v[22:25], v[174:177], v[198:201], v[22:25]
	v_mfma_f32_16x16x32_bf16 v[94:97], v[166:169], v[206:209], v[94:97]
	v_mfma_f32_16x16x32_bf16 v[30:33], v[174:177], v[206:209], v[30:33]
	v_mfma_f32_16x16x32_bf16 v[98:101], v[170:173], v[186:189], v[98:101]
	v_mfma_f32_16x16x32_bf16 v[34:37], v[178:181], v[186:189], v[34:37]
	v_mfma_f32_16x16x32_bf16 v[82:85], v[170:173], v[194:197], v[82:85]
	v_mfma_f32_16x16x32_bf16 v[18:21], v[178:181], v[194:197], v[18:21]
	v_mfma_f32_16x16x32_bf16 v[86:89], v[170:173], v[202:205], v[86:89]
	v_mfma_f32_16x16x32_bf16 v[22:25], v[178:181], v[202:205], v[22:25]
	v_mfma_f32_16x16x32_bf16 v[94:97], v[170:173], v[210:213], v[94:97]
	v_mfma_f32_16x16x32_bf16 v[30:33], v[178:181], v[210:213], v[30:33]
	s_barrier
	s_add_i32 s50, s73, s15
	v_lshl_add_u64 v[214:215], s[52:53], 0, v[228:229]
	s_mov_b32 m0, s50
	ds_read_b128 v[182:185], v149 offset:16384
	ds_read_b128 v[186:189], v149 offset:17408
	ds_read_b128 v[190:193], v149 offset:18432
	ds_read_b128 v[194:197], v149 offset:19456
	ds_read_b128 v[198:201], v149 offset:20480
	ds_read_b128 v[202:205], v149 offset:21504
	ds_read_b128 v[206:209], v149 offset:22528
	ds_read_b128 v[210:213], v149 offset:23552
	global_load_lds_dwordx4 v[214:215], off
	s_add_i32 m0, s50, 0x2000
	s_add_u32 s50, s52, 0x40000
	v_lshl_add_u64 v[216:217], s[52:53], 0, v[232:233]
	s_addc_u32 s51, s53, 0
	s_add_i32 s78, s74, s15
	global_load_lds_dwordx4 v[216:217], off
	v_lshl_add_u64 v[218:219], s[50:51], 0, v[228:229]
	s_mov_b32 m0, s78
	v_lshl_add_u64 v[220:221], s[54:55], 0, v[230:231]
	global_load_lds_dwordx4 v[218:219], off
	v_lshl_add_u64 v[218:219], s[50:51], 0, v[232:233]
	s_add_i32 m0, s78, 0x2000
	s_nop 0
	global_load_lds_dwordx4 v[218:219], off
	v_lshl_add_u64 v[218:219], s[54:55], 0, v[226:227]
	s_mov_b32 m0, s60
	s_nop 0
	global_load_lds_dwordx4 v[218:219], off
	s_mov_b32 m0, s61
	s_nop 0
	global_load_lds_dwordx4 v[220:221], off
	s_waitcnt vmcnt(8)
	s_waitcnt lgkmcnt(0)
	s_barrier
	s_waitcnt lgkmcnt(0)
	v_mfma_f32_16x16x32_bf16 v[90:93], v[150:153], v[182:185], v[90:93]
	v_mfma_f32_16x16x32_bf16 v[26:29], v[158:161], v[182:185], v[26:29]
	v_mfma_f32_16x16x32_bf16 v[102:105], v[150:153], v[190:193], v[102:105]
	v_mfma_f32_16x16x32_bf16 v[38:41], v[158:161], v[190:193], v[38:41]
	v_mfma_f32_16x16x32_bf16 v[106:109], v[150:153], v[198:201], v[106:109]
	v_mfma_f32_16x16x32_bf16 v[42:45], v[158:161], v[198:201], v[42:45]
	v_mfma_f32_16x16x32_bf16 v[110:113], v[150:153], v[206:209], v[110:113]
	v_mfma_f32_16x16x32_bf16 v[46:49], v[158:161], v[206:209], v[46:49]
	v_mfma_f32_16x16x32_bf16 v[90:93], v[154:157], v[186:189], v[90:93]
	v_mfma_f32_16x16x32_bf16 v[26:29], v[162:165], v[186:189], v[26:29]
	v_mfma_f32_16x16x32_bf16 v[102:105], v[154:157], v[194:197], v[102:105]
	v_mfma_f32_16x16x32_bf16 v[38:41], v[162:165], v[194:197], v[38:41]
	v_mfma_f32_16x16x32_bf16 v[106:109], v[154:157], v[202:205], v[106:109]
	v_mfma_f32_16x16x32_bf16 v[42:45], v[162:165], v[202:205], v[42:45]
	v_mfma_f32_16x16x32_bf16 v[110:113], v[154:157], v[210:213], v[110:113]
	v_mfma_f32_16x16x32_bf16 v[46:49], v[162:165], v[210:213], v[46:49]
	v_mfma_f32_16x16x32_bf16 v[114:117], v[166:169], v[182:185], v[114:117]
	v_mfma_f32_16x16x32_bf16 v[50:53], v[174:177], v[182:185], v[50:53]
	v_mfma_f32_16x16x32_bf16 v[118:121], v[166:169], v[190:193], v[118:121]
	v_mfma_f32_16x16x32_bf16 v[54:57], v[174:177], v[190:193], v[54:57]
	v_mfma_f32_16x16x32_bf16 v[122:125], v[166:169], v[198:201], v[122:125]
	v_mfma_f32_16x16x32_bf16 v[58:61], v[174:177], v[198:201], v[58:61]
	v_mfma_f32_16x16x32_bf16 v[126:129], v[166:169], v[206:209], v[126:129]
	v_mfma_f32_16x16x32_bf16 v[62:65], v[174:177], v[206:209], v[62:65]
	v_mfma_f32_16x16x32_bf16 v[114:117], v[170:173], v[186:189], v[114:117]
	v_mfma_f32_16x16x32_bf16 v[50:53], v[178:181], v[186:189], v[50:53]
	v_mfma_f32_16x16x32_bf16 v[118:121], v[170:173], v[194:197], v[118:121]
	v_mfma_f32_16x16x32_bf16 v[54:57], v[178:181], v[194:197], v[54:57]
	v_mfma_f32_16x16x32_bf16 v[122:125], v[170:173], v[202:205], v[122:125]
	v_mfma_f32_16x16x32_bf16 v[58:61], v[178:181], v[202:205], v[58:61]
	v_mfma_f32_16x16x32_bf16 v[126:129], v[170:173], v[210:213], v[126:129]
	v_mfma_f32_16x16x32_bf16 v[62:65], v[178:181], v[210:213], v[62:65]
	s_barrier
	s_add_i32 s78, 0, 0x18000
	s_add_i32 s79, 0, 0x1c000
	v_add_u32_e32 v162, s78, v140
	v_add_u32_e32 v178, s79, v140
	ds_read_b128 v[150:153], v162
	ds_read_b128 v[154:157], v162 offset:1024
	ds_read_b128 v[158:161], v162 offset:2048
	ds_read_b128 v[162:165], v162 offset:3072
	ds_read_b128 v[166:169], v178
	ds_read_b128 v[170:173], v178 offset:1024
	ds_read_b128 v[174:177], v178 offset:2048
	ds_read_b128 v[178:181], v178 offset:3072
	s_add_u32 s50, s54, 0x40000
	s_addc_u32 s51, s55, 0
	s_mov_b32 m0, s62
	v_lshl_add_u64 v[222:223], s[50:51], 0, v[226:227]
	ds_read_b128 v[182:185], v149 offset:32768
	ds_read_b128 v[186:189], v149 offset:33792
	ds_read_b128 v[190:193], v149 offset:34816
	ds_read_b128 v[194:197], v149 offset:35840
	ds_read_b128 v[198:201], v149 offset:36864
	ds_read_b128 v[202:205], v149 offset:37888
	ds_read_b128 v[206:209], v149 offset:38912
	ds_read_b128 v[210:213], v149 offset:39936
	global_load_lds_dwordx4 v[222:223], off
	v_lshl_add_u64 v[222:223], s[50:51], 0, v[230:231]
	s_mov_b32 m0, s63
	s_nop 0
	global_load_lds_dwordx4 v[222:223], off
	s_waitcnt vmcnt(8)
	s_waitcnt lgkmcnt(0)
	s_barrier
	s_waitcnt lgkmcnt(0)
	v_mfma_f32_16x16x32_bf16 v[78:81], v[150:153], v[182:185], v[78:81]
	v_mfma_f32_16x16x32_bf16 v[14:17], v[158:161], v[182:185], v[14:17]
	v_mfma_f32_16x16x32_bf16 v[66:69], v[150:153], v[190:193], v[66:69]
	v_mfma_f32_16x16x32_bf16 v[2:5], v[158:161], v[190:193], v[2:5]
	v_mfma_f32_16x16x32_bf16 v[70:73], v[150:153], v[198:201], v[70:73]
	v_mfma_f32_16x16x32_bf16 v[6:9], v[158:161], v[198:201], v[6:9]
	v_mfma_f32_16x16x32_bf16 v[74:77], v[150:153], v[206:209], v[74:77]
	v_mfma_f32_16x16x32_bf16 v[10:13], v[158:161], v[206:209], v[10:13]
	v_mfma_f32_16x16x32_bf16 v[78:81], v[154:157], v[186:189], v[78:81]
	v_mfma_f32_16x16x32_bf16 v[14:17], v[162:165], v[186:189], v[14:17]
	v_mfma_f32_16x16x32_bf16 v[66:69], v[154:157], v[194:197], v[66:69]
	v_mfma_f32_16x16x32_bf16 v[2:5], v[162:165], v[194:197], v[2:5]
	v_mfma_f32_16x16x32_bf16 v[70:73], v[154:157], v[202:205], v[70:73]
	v_mfma_f32_16x16x32_bf16 v[6:9], v[162:165], v[202:205], v[6:9]
	v_mfma_f32_16x16x32_bf16 v[74:77], v[154:157], v[210:213], v[74:77]
	v_mfma_f32_16x16x32_bf16 v[10:13], v[162:165], v[210:213], v[10:13]
	v_mfma_f32_16x16x32_bf16 v[98:101], v[166:169], v[182:185], v[98:101]
	v_mfma_f32_16x16x32_bf16 v[34:37], v[174:177], v[182:185], v[34:37]
	v_mfma_f32_16x16x32_bf16 v[82:85], v[166:169], v[190:193], v[82:85]
	v_mfma_f32_16x16x32_bf16 v[18:21], v[174:177], v[190:193], v[18:21]
	v_mfma_f32_16x16x32_bf16 v[86:89], v[166:169], v[198:201], v[86:89]
	v_mfma_f32_16x16x32_bf16 v[22:25], v[174:177], v[198:201], v[22:25]
	v_mfma_f32_16x16x32_bf16 v[94:97], v[166:169], v[206:209], v[94:97]
	v_mfma_f32_16x16x32_bf16 v[30:33], v[174:177], v[206:209], v[30:33]
	v_mfma_f32_16x16x32_bf16 v[98:101], v[170:173], v[186:189], v[98:101]
	v_mfma_f32_16x16x32_bf16 v[34:37], v[178:181], v[186:189], v[34:37]
	v_mfma_f32_16x16x32_bf16 v[82:85], v[170:173], v[194:197], v[82:85]
	v_mfma_f32_16x16x32_bf16 v[18:21], v[178:181], v[194:197], v[18:21]
	v_mfma_f32_16x16x32_bf16 v[86:89], v[170:173], v[202:205], v[86:89]
	v_mfma_f32_16x16x32_bf16 v[22:25], v[178:181], v[202:205], v[22:25]
	v_mfma_f32_16x16x32_bf16 v[94:97], v[170:173], v[210:213], v[94:97]
	v_mfma_f32_16x16x32_bf16 v[30:33], v[178:181], v[210:213], v[30:33]
	s_barrier
	s_add_i32 s50, s78, s15
	v_lshl_add_u64 v[214:215], v[214:215], 0, s[8:9]
	s_mov_b32 m0, s50
	ds_read_b128 v[182:185], v149 offset:49152
	ds_read_b128 v[186:189], v149 offset:50176
	ds_read_b128 v[190:193], v149 offset:51200
	ds_read_b128 v[194:197], v149 offset:52224
	ds_read_b128 v[198:201], v149 offset:53248
	ds_read_b128 v[202:205], v149 offset:54272
	ds_read_b128 v[206:209], v149 offset:55296
	ds_read_b128 v[210:213], v149 offset:56320
	global_load_lds_dwordx4 v[214:215], off
	s_add_i32 m0, s50, 0x2000
	s_add_u32 s50, s52, 0x40080
	v_lshl_add_u64 v[214:215], v[216:217], 0, s[8:9]
	s_addc_u32 s51, s53, 0
	s_add_i32 s52, s79, s15
	global_load_lds_dwordx4 v[214:215], off
	v_lshl_add_u64 v[214:215], s[50:51], 0, v[228:229]
	s_mov_b32 m0, s52
	s_nop 0
	global_load_lds_dwordx4 v[214:215], off
	v_lshl_add_u64 v[214:215], s[50:51], 0, v[232:233]
	s_add_i32 m0, s52, 0x2000
	s_nop 0
	global_load_lds_dwordx4 v[214:215], off
	v_lshl_add_u64 v[214:215], v[218:219], 0, s[8:9]
	s_mov_b32 m0, s68
	s_nop 0
	global_load_lds_dwordx4 v[214:215], off
	v_lshl_add_u64 v[214:215], v[220:221], 0, s[8:9]
	s_mov_b32 m0, s69
	s_nop 0
	global_load_lds_dwordx4 v[214:215], off
	s_waitcnt vmcnt(8)
	s_waitcnt lgkmcnt(0)
	s_barrier
	s_waitcnt lgkmcnt(0)
	v_mfma_f32_16x16x32_bf16 v[90:93], v[150:153], v[182:185], v[90:93]
	v_mfma_f32_16x16x32_bf16 v[26:29], v[158:161], v[182:185], v[26:29]
	v_mfma_f32_16x16x32_bf16 v[102:105], v[150:153], v[190:193], v[102:105]
	v_mfma_f32_16x16x32_bf16 v[38:41], v[158:161], v[190:193], v[38:41]
	v_mfma_f32_16x16x32_bf16 v[106:109], v[150:153], v[198:201], v[106:109]
	v_mfma_f32_16x16x32_bf16 v[42:45], v[158:161], v[198:201], v[42:45]
	v_mfma_f32_16x16x32_bf16 v[110:113], v[150:153], v[206:209], v[110:113]
	v_mfma_f32_16x16x32_bf16 v[46:49], v[158:161], v[206:209], v[46:49]
	v_mfma_f32_16x16x32_bf16 v[90:93], v[154:157], v[186:189], v[90:93]
	v_mfma_f32_16x16x32_bf16 v[26:29], v[162:165], v[186:189], v[26:29]
	v_mfma_f32_16x16x32_bf16 v[102:105], v[154:157], v[194:197], v[102:105]
	v_mfma_f32_16x16x32_bf16 v[38:41], v[162:165], v[194:197], v[38:41]
	v_mfma_f32_16x16x32_bf16 v[106:109], v[154:157], v[202:205], v[106:109]
	v_mfma_f32_16x16x32_bf16 v[42:45], v[162:165], v[202:205], v[42:45]
	v_mfma_f32_16x16x32_bf16 v[110:113], v[154:157], v[210:213], v[110:113]
	v_mfma_f32_16x16x32_bf16 v[46:49], v[162:165], v[210:213], v[46:49]
	v_mfma_f32_16x16x32_bf16 v[114:117], v[166:169], v[182:185], v[114:117]
	v_mfma_f32_16x16x32_bf16 v[50:53], v[174:177], v[182:185], v[50:53]
	v_mfma_f32_16x16x32_bf16 v[118:121], v[166:169], v[190:193], v[118:121]
	v_mfma_f32_16x16x32_bf16 v[54:57], v[174:177], v[190:193], v[54:57]
	v_mfma_f32_16x16x32_bf16 v[122:125], v[166:169], v[198:201], v[122:125]
	v_mfma_f32_16x16x32_bf16 v[58:61], v[174:177], v[198:201], v[58:61]
	v_mfma_f32_16x16x32_bf16 v[126:129], v[166:169], v[206:209], v[126:129]
	v_mfma_f32_16x16x32_bf16 v[62:65], v[174:177], v[206:209], v[62:65]
	v_mfma_f32_16x16x32_bf16 v[114:117], v[170:173], v[186:189], v[114:117]
	v_mfma_f32_16x16x32_bf16 v[50:53], v[178:181], v[186:189], v[50:53]
	v_mfma_f32_16x16x32_bf16 v[118:121], v[170:173], v[194:197], v[118:121]
	v_mfma_f32_16x16x32_bf16 v[54:57], v[178:181], v[194:197], v[54:57]
	v_mfma_f32_16x16x32_bf16 v[122:125], v[170:173], v[202:205], v[122:125]
	v_mfma_f32_16x16x32_bf16 v[58:61], v[178:181], v[202:205], v[58:61]
	v_mfma_f32_16x16x32_bf16 v[126:129], v[170:173], v[210:213], v[126:129]
	v_mfma_f32_16x16x32_bf16 v[62:65], v[178:181], v[210:213], v[62:65]
	s_barrier
	s_add_u32 s34, s34, 0x100
	s_addc_u32 s35, s35, 0
	s_add_u32 s21, s21, 0x100
	s_addc_u32 s23, s23, 0
	s_cmp_ge_i32 s77, s66
	s_mov_b32 s52, s77
	s_cbranch_scc0 .LBB0_872
